# static s_setprio 1 for waves 4-7 across the attention phase (reset at phase exit)
# baseline (speedup 1.0000x reference)
; #define LAS __attribute__((address_space(3)))
; #define PH_BEGIN(k) if (lo <= ph && ph < hi) { if constexpr ((EN >> (k)) & 1) for (int rep_ = 0; rep_ < ((((REP) >> (k)) & 1) ? 2 : 1); ++rep_) {
; __global__ void __launch_bounds__(512, 2) mega_fwd(Args a) {
;     ...
;         PH_BEGIN(3)
;         {
;             unsigned* qc = ctl + 512 + l;
;             volatile LAS int* qslot = (volatile LAS int*)(lds + LDS_BYTES - 32);
;             for (;;) {
;                 if (tid == 0) *qslot = (int)atomicAdd(qc, 1u);
;                 __syncthreads();
;                 const int it = __builtin_amdgcn_readfirstlane(*qslot);
;                 __syncthreads();
;                 if (it >= 768) break;
.Lcve_done:
	v_readfirstlane_b32 s100, v166
	s_nop 3
	s_lshr_b32 s100, s100, 6
	s_cmp_ge_u32 s100, 4
	s_cbranch_scc0 .Lattn_prio_skip
	s_setprio 1

; __device__ __forceinline__ unsigned xb_add(unsigned* p, unsigned v) { return __hip_atomic_fetch_add(p, v, __ATOMIC_RELAXED, __HIP_MEMORY_SCOPE_AGENT); }
; __device__ __forceinline__ void xcd_barrier(const XcdBarrier& b) {
;     asm volatile("s_waitcnt vmcnt(0)" ::: "memory");
;     __syncthreads();
;     if (threadIdx.x == 0) {
;         unsigned* bar = b.bar;
;         __builtin_amdgcn_s_waitcnt(0);
;         unsigned nloc = b.st[0], nx = b.st[1];
;         if (nloc == 0u) { xcd_barrier_complete(bar, b.x, nloc, nx); b.st[0] = nloc; b.st[1] = nx; }
;         const unsigned old = xb_add(&bar[XB_XSUB(b.x)], 1u);
;         const unsigned gen = old / nloc;
;         if (old + 1u == (gen + 1u) * nloc) {
.LBB0_862:
	s_setprio 0
	v_readlane_b32 s0, v251, 3
	s_add_i32 s28, s68, 3
	v_readlane_b32 s1, v251, 4
	s_cmp_lt_i32 s28, s1
	s_cbranch_scc0 .LBB0_875
	v_readlane_b32 s0, v254, 41
	v_readlane_b32 s72, v251, 6
	s_cmp_lg_u32 s0, 0
	v_readlane_b32 s73, v251, 7
	s_cbranch_scc0 .LBB0_876
	s_waitcnt vmcnt(0)
	s_barrier
	s_and_saveexec_b64 s[0:1], s[84:85]
	s_cbranch_execz .LBB0_918
	v_readlane_b32 s2, v254, 15
	s_waitcnt vmcnt(0) expcnt(0) lgkmcnt(0)
	s_nop 0
	v_mov_b32_e32 v0, s2
	ds_read_b32 v3, v0
	v_readlane_b32 s2, v254, 16
	s_waitcnt lgkmcnt(0)
	v_cmp_ne_u32_e32 vcc, 0, v3
	v_mov_b32_e32 v0, s2
	ds_read_b32 v2, v0
	s_cbranch_vccnz .LBB0_882
	s_mov_b32 s8, 1
	s_branch .LBB0_868
